# attention unit epilogue de-serialised: 8 l-reads in flight then 16 rcp, 4 transposed O reads in flight with counted waits before the 16-byte stores
# speedup vs baseline: 1.0039x; 1.0016x over previous
.LBB0_324:
	s_or_b64 exec, exec, s[8:9]
	s_waitcnt lgkmcnt(0)
	v_add_u32_e32 v34, 0xc080, v50
	ds_read2_b32 v[52:53], v34 offset0:0 offset1:1
	ds_read2_b32 v[54:55], v34 offset0:2 offset1:3
	ds_read2_b32 v[56:57], v34 offset0:8 offset1:9
	ds_read2_b32 v[58:59], v34 offset0:10 offset1:11
	ds_read2_b32 v[60:61], v34 offset0:16 offset1:17
	ds_read2_b32 v[62:63], v34 offset0:18 offset1:19
	ds_read2_b32 v[64:65], v34 offset0:24 offset1:25
	ds_read2_b32 v[66:67], v34 offset0:26 offset1:27
	v_readlane_b32 s3, v255, 54
	s_add_u32 s3, s3, s12
	v_readlane_b32 s8, v255, 55
	s_addc_u32 s8, s8, s13
	s_lshl_b32 s9, s37, 12
	s_add_i32 s9, s66, s9
	v_lshlrev_b32_e32 v0, 1, v0
	s_lshl_b64 s[10:11], s[14:15], 1
	s_add_u32 s10, s3, s10
	s_addc_u32 s11, s8, s11
	v_lshlrev_b32_e32 v50, 1, v204
	v_add3_u32 v0, s9, v0, v50
	s_waitcnt lgkmcnt(0)
	v_rcp_f32_e32 v36, v52
	v_rcp_f32_e32 v37, v53
	v_rcp_f32_e32 v38, v54
	v_rcp_f32_e32 v39, v55
	v_rcp_f32_e32 v40, v56
	v_rcp_f32_e32 v41, v57
	v_rcp_f32_e32 v42, v58
	v_rcp_f32_e32 v43, v59
	v_rcp_f32_e32 v44, v60
	v_rcp_f32_e32 v45, v61
	v_rcp_f32_e32 v46, v62
	v_rcp_f32_e32 v47, v63
	v_rcp_f32_e32 v48, v64
	v_rcp_f32_e32 v49, v65
	v_rcp_f32_e32 v34, v66
	v_rcp_f32_e32 v35, v67
	v_mul_f32_e32 v2, v2, v36
	v_cvt_pk_bf16_f32 v2, v2, s0
	v_mul_f32_e32 v18, v18, v36
	v_cvt_pk_bf16_f32 v18, v18, s0
	ds_write_b16 v0, v2 offset:51264
	v_mul_f32_e32 v2, v19, v37
	v_cvt_pk_bf16_f32 v2, v2, s0
	ds_write_b16 v0, v2 offset:51328
	v_mul_f32_e32 v2, v3, v37
	v_cvt_pk_bf16_f32 v2, v2, s0
	ds_write_b16 v0, v2 offset:51392
	v_mul_f32_e32 v2, v20, v38
	v_cvt_pk_bf16_f32 v2, v2, s0
	ds_write_b16 v0, v2 offset:51456
	v_mul_f32_e32 v2, v4, v38
	v_cvt_pk_bf16_f32 v2, v2, s0
	ds_write_b16 v0, v2 offset:51520
	v_mul_f32_e32 v2, v21, v39
	v_cvt_pk_bf16_f32 v2, v2, s0
	ds_write_b16 v0, v2 offset:51584
	v_mul_f32_e32 v2, v5, v39
	v_cvt_pk_bf16_f32 v2, v2, s0
	ds_write_b16 v0, v2 offset:51648
	v_mul_f32_e32 v2, v22, v40
	v_cvt_pk_bf16_f32 v2, v2, s0
	ds_write_b16 v0, v2 offset:52224
	v_mul_f32_e32 v2, v6, v40
	v_cvt_pk_bf16_f32 v2, v2, s0
	ds_write_b16 v0, v2 offset:52288
	v_mul_f32_e32 v2, v23, v41
	v_cvt_pk_bf16_f32 v2, v2, s0
	ds_write_b16 v0, v2 offset:52352
	v_mul_f32_e32 v2, v7, v41
	v_cvt_pk_bf16_f32 v2, v2, s0
	ds_write_b16 v0, v2 offset:52416
	v_mul_f32_e32 v2, v24, v42
	v_cvt_pk_bf16_f32 v2, v2, s0
	ds_write_b16 v0, v2 offset:52480
	v_mul_f32_e32 v2, v8, v42
	v_cvt_pk_bf16_f32 v2, v2, s0
	ds_write_b16 v0, v2 offset:52544
	v_mul_f32_e32 v2, v25, v43
	v_cvt_pk_bf16_f32 v2, v2, s0
	ds_write_b16 v0, v2 offset:52608
	v_mul_f32_e32 v2, v9, v43
	v_cvt_pk_bf16_f32 v2, v2, s0
	ds_write_b16 v0, v2 offset:52672
	v_mul_f32_e32 v2, v26, v44
	v_cvt_pk_bf16_f32 v2, v2, s0
	ds_write_b16 v0, v2 offset:53248
	v_mul_f32_e32 v2, v10, v44
	v_cvt_pk_bf16_f32 v2, v2, s0
	ds_write_b16 v0, v2 offset:53312
	v_mul_f32_e32 v2, v27, v45
	v_cvt_pk_bf16_f32 v2, v2, s0
	ds_write_b16 v0, v2 offset:53376
	v_mul_f32_e32 v2, v11, v45
	v_cvt_pk_bf16_f32 v2, v2, s0
	ds_write_b16 v0, v2 offset:53440
	v_mul_f32_e32 v2, v28, v46
	v_cvt_pk_bf16_f32 v2, v2, s0
	ds_write_b16 v0, v2 offset:53504
	v_mul_f32_e32 v2, v12, v46
	v_cvt_pk_bf16_f32 v2, v2, s0
	ds_write_b16 v0, v2 offset:53568
	v_mul_f32_e32 v2, v29, v47
	v_cvt_pk_bf16_f32 v2, v2, s0
	ds_write_b16 v0, v2 offset:53632
	v_mul_f32_e32 v2, v13, v47
	v_cvt_pk_bf16_f32 v2, v2, s0
	ds_write_b16 v0, v2 offset:53696
	v_mul_f32_e32 v2, v30, v48
	v_cvt_pk_bf16_f32 v2, v2, s0
	ds_write_b16 v0, v2 offset:54272
	v_mul_f32_e32 v2, v14, v48
	v_cvt_pk_bf16_f32 v2, v2, s0
	ds_write_b16 v0, v2 offset:54336
	v_mul_f32_e32 v2, v31, v49
	v_cvt_pk_bf16_f32 v2, v2, s0
	ds_write_b16 v0, v2 offset:54400
	v_mul_f32_e32 v2, v15, v49
	v_cvt_pk_bf16_f32 v2, v2, s0
	ds_write_b16 v0, v2 offset:54464
	v_mul_f32_e32 v2, v32, v34
	v_cvt_pk_bf16_f32 v2, v2, s0
	ds_write_b16 v0, v2 offset:54528
	v_mul_f32_e32 v2, v16, v34
	v_cvt_pk_bf16_f32 v2, v2, s0
	ds_write_b16 v0, v2 offset:54592
	v_mul_f32_e32 v2, v33, v35
	v_cvt_pk_bf16_f32 v2, v2, s0
	ds_write_b16 v0, v2 offset:54656
	v_mul_f32_e32 v2, v17, v35
	v_cvt_pk_bf16_f32 v2, v2, s0
	ds_write_b16 v0, v18 offset:51200
	ds_write_b16 v0, v2 offset:54720
	v_lshlrev_b32_e32 v0, 1, v203
	v_and_b32_e32 v0, 0x70, v0
	v_lshrrev_b32_e32 v10, 3, v202
	v_add_u32_e32 v11, s9, v0
	s_waitcnt lgkmcnt(0)
	v_lshl_add_u64 v[6:7], s[10:11], 0, v[0:1]
	v_lshl_add_u32 v0, v10, 7, v11
	ds_read_b128 v[2:5], v0 offset:51200
	ds_read_b128 v[52:55], v0 offset:52224
	ds_read_b128 v[56:59], v0 offset:53248
	ds_read_b128 v[60:63], v0 offset:54272
	v_lshlrev_b32_e32 v0, 10, v10
	v_lshl_add_u64 v[8:9], v[6:7], 0, v[0:1]
	s_mov_b32 s8, 0x2000
	s_mov_b32 s9, 0
	v_lshl_add_u64 v[12:13], v[8:9], 0, s[8:9]
	v_lshl_add_u64 v[14:15], v[12:13], 0, s[8:9]
	v_lshl_add_u64 v[16:17], v[14:15], 0, s[8:9]
	s_waitcnt lgkmcnt(3)
	global_store_dwordx4 v[8:9], v[2:5], off
	s_waitcnt lgkmcnt(2)
	global_store_dwordx4 v[12:13], v[52:55], off
	s_waitcnt lgkmcnt(1)
	global_store_dwordx4 v[14:15], v[56:59], off
	s_waitcnt lgkmcnt(0)
	global_store_dwordx4 v[16:17], v[60:63], off
	s_waitcnt lgkmcnt(0)
	s_barrier
